# attention loop: LDS read addresses of the next step computed ahead of the barrier (two address register pairs), and no VALU behind the first three MFMAs after the barrier (bare MFMA head), 5 VALU per
# baseline (speedup 1.0000x reference)
; __device__ __forceinline__ void attn_unit(const Args& a, int l, int b, int h, int R0, bool special, LAS unsigned char* lds, float kb, int wv, bool pre, bool hasn, int nb, int nh, int nR0) {
;     ...
;     float mref = fixed ? kb * qnorm : 0.f, lsum = 0.f; f32x16 o0 = {}, o1 = {}, pc0 = {}, pc1 = {}, negm;
; #pragma unroll
;     for (int r = 0; r < 16; ++r) negm[r] = -mref;
.Lfa_entry:
	v_mov_b32_e32 v210, 0
	v_mov_b32_e32 v211, 0
	v_mov_b32_e32 v212, 0
	v_mov_b32_e32 v213, 0
	v_mov_b32_e32 v214, 0
	v_mov_b32_e32 v215, 0
	v_mov_b32_e32 v216, 0
	v_mov_b32_e32 v217, 0
	v_mov_b32_e32 v218, 0
	v_mov_b32_e32 v219, 0
	v_mov_b32_e32 v220, 0
	v_mov_b32_e32 v221, 0
	v_mov_b32_e32 v222, 0
	v_mov_b32_e32 v223, 0
	v_mov_b32_e32 v224, 0
	v_mov_b32_e32 v225, 0
	v_mov_b32_e32 v234, 0
	v_mov_b32_e32 v235, 0
	v_mov_b32_e32 v236, 0
	v_mov_b32_e32 v237, 0
	v_mov_b32_e32 v238, 0
	v_mov_b32_e32 v239, 0
	v_mov_b32_e32 v240, 0
	v_mov_b32_e32 v241, 0
	v_mov_b32_e32 v248, 0
	v_mov_b32_e32 v249, 0
	v_mov_b32_e32 v250, 0
	v_mov_b32_e32 v251, 0
	s_mov_b32 s0, 0xd000
	v_add3_u32 v247, v26, v28, s0
	v_readfirstlane_b32 s22, v20
	v_readfirstlane_b32 s23, v21
	s_nop 1
	v_subrev_u32_e32 v0, s22, v20
	v_subrev_u32_e32 v14, s22, v18
	s_add_u32 s22, s22, 0x220c000
	s_addc_u32 s23, s23, 0
	v_readfirstlane_b32 s34, v22
	v_readfirstlane_b32 s35, v23
	s_nop 1
	v_subrev_u32_e32 v15, s34, v22
	v_subrev_u32_e32 v197, s34, v24
	s_add_u32 s34, s34, 0x1b900180
	s_addc_u32 s35, s35, 0
	s_and_b32 s88, s87, 3
	s_mulk_i32 s88, 0x3400
	s_add_i32 s90, s87, 1
	s_and_b32 s90, s90, 3
	s_mulk_i32 s90, 0x3400
	s_mov_b32 s32, 0
	s_movk_i32 s30, 0x2400
	s_mov_b32 s31, 0
	v_add_u32_e32 v230, s88, v190
	v_add_u32_e32 v231, s30, v247
	s_add_i32 s24, s77, -1
	s_add_i32 s0, s73, -3
	s_min_i32 s24, s24, s0
	s_add_i32 s0, s74, 1
	s_ashr_i32 s0, s0, 6
	s_min_i32 s24, s24, s0
	s_add_i32 s76, s87, 2
	s_cmp_le_i32 s76, s24
	s_cbranch_scc0 .Lfa_loop
.Lfa_sloop:
	s_add_i32 s76, s87, 2
	ds_read_b128 v[2:5], v230
	ds_read_b128 v[6:9], v230 offset:6656
	ds_read_b128 v[10:13], v230 offset:32
	ds_read_b128 v[198:201], v230 offset:6688
	ds_read_b128 v[202:205], v230 offset:64
	ds_read_b128 v[206:209], v230 offset:6720
	v_mfma_f32_32x32x16_bf16 v[64:79], v[210:213], v[234:237], v[64:79]
	v_mfma_f32_32x32x16_bf16 v[48:63], v[214:217], v[234:237], v[48:63]
	s_xor_b32 s1, s88, 0x6800
	s_add_i32 m0, s1, s66
	s_and_b64 vcc, exec, s[40:41]
	global_load_lds_dwordx4 v0, s[22:23]
	s_cbranch_vccnz .Lfa_as_nok
	s_add_i32 m0, s1, s78
	s_and_b64 vcc, exec, s[42:43]
	global_load_lds_dwordx4 v14, s[22:23]
.Lfa_as_nok:
	s_add_u32 s22, s22, 0x3000
	s_addc_u32 s23, s23, 0
	v_mfma_f32_32x32x16_bf16 v[64:79], v[218:221], v[238:241], v[64:79]
	ds_read_b128 v[210:213], v230 offset:96
	ds_read_b128 v[214:217], v230 offset:6752
	v_mfma_f32_32x32x16_bf16 v[48:63], v[222:225], v[238:241], v[48:63]
	ds_read_b128 v[218:221], v230 offset:128
	ds_read_b128 v[222:225], v230 offset:6784
	ds_read_b128 v[234:237], v230 offset:160
	ds_read_b128 v[238:241], v230 offset:6816
	s_add_i32 s1, s31, s66
	s_add_i32 m0, s1, 0xd000
	s_and_b64 vcc, exec, s[42:43]
	global_load_lds_dwordx4 v15, s[34:35]
	s_cbranch_vccnz .Lfa_as_nov
	s_add_i32 m0, s31, 0xf000
	s_nop 0
	global_load_lds_dwordx4 v197, s[34:35]
; __device__ __forceinline__ void attn_unit(const Args& a, int l, int b, int h, int R0, bool special, LAS unsigned char* lds, float kb, int wv, bool pre, bool hasn, int nb, int nh, int nR0) {
;     ...
;     if (wave >= 4) __builtin_amdgcn_s_setprio(1);
.Lfa_as_nov:
	s_add_u32 s34, s34, 0x80
	s_addc_u32 s35, s35, 0
	v_exp_f32_e32 v96, v96
	v_exp_f32_e32 v97, v97
	v_add_f32_e32 v248, v248, v96
	v_exp_f32_e32 v98, v98
	v_add_f32_e32 v249, v249, v97
	s_waitcnt lgkmcnt(10)
	v_mfma_f32_32x32x16_bf16 v[128:143], v[2:5], v[156:159], v[32:47]
	v_exp_f32_e32 v99, v99
	v_add_f32_e32 v250, v250, v98
	v_exp_f32_e32 v100, v100
	v_add_f32_e32 v251, v251, v99
	v_exp_f32_e32 v101, v101
	v_mfma_f32_32x32x16_bf16 v[112:127], v[6:9], v[156:159], v[32:47]
	ds_read_b128 v[2:5], v231
	ds_read_b128 v[6:9], v231 offset:4608
	v_add_f32_e32 v248, v248, v100
	v_exp_f32_e32 v102, v102
	v_add_f32_e32 v249, v249, v101
	v_exp_f32_e32 v103, v103
	v_add_f32_e32 v250, v250, v102
	s_waitcnt lgkmcnt(10)
	v_mfma_f32_32x32x16_bf16 v[128:143], v[10:13], v[160:163], v[128:143]
	v_add_f32_e32 v251, v251, v103
	v_cvt_pk_bf16_f32 v96, v96, v97
	v_cvt_pk_bf16_f32 v97, v98, v99
	v_cvt_pk_bf16_f32 v98, v100, v101
	v_cvt_pk_bf16_f32 v99, v102, v103
	v_mfma_f32_32x32x16_bf16 v[112:127], v[198:201], v[160:163], v[112:127]
	ds_read_b128 v[10:13], v231 offset:32
	ds_read_b128 v[198:201], v231 offset:4640
	v_exp_f32_e32 v104, v104
	v_exp_f32_e32 v105, v105
	v_add_f32_e32 v248, v248, v104
	v_exp_f32_e32 v106, v106
	v_add_f32_e32 v249, v249, v105
	s_waitcnt lgkmcnt(10)
	v_mfma_f32_32x32x16_bf16 v[128:143], v[202:205], v[164:167], v[128:143]
	v_exp_f32_e32 v107, v107
	v_add_f32_e32 v250, v250, v106
	v_exp_f32_e32 v108, v108
	v_add_f32_e32 v251, v251, v107
	v_exp_f32_e32 v109, v109
	v_mfma_f32_32x32x16_bf16 v[112:127], v[206:209], v[164:167], v[112:127]
	v_add_f32_e32 v248, v248, v108
	v_exp_f32_e32 v110, v110
	v_add_f32_e32 v249, v249, v109
	v_exp_f32_e32 v111, v111
	v_add_f32_e32 v250, v250, v110
	s_waitcnt lgkmcnt(8)
	v_mfma_f32_32x32x16_bf16 v[128:143], v[210:213], v[144:147], v[128:143]
	v_add_f32_e32 v251, v251, v111
	v_cvt_pk_bf16_f32 v104, v104, v105
	v_cvt_pk_bf16_f32 v105, v106, v107
	v_cvt_pk_bf16_f32 v106, v108, v109
	v_cvt_pk_bf16_f32 v107, v110, v111
	v_mfma_f32_32x32x16_bf16 v[112:127], v[214:217], v[144:147], v[112:127]
	ds_read_b128 v[210:213], v231 offset:64
	ds_read_b128 v[214:217], v231 offset:4672
	v_exp_f32_e32 v80, v80
	v_exp_f32_e32 v81, v81
	v_add_f32_e32 v248, v248, v80
	v_exp_f32_e32 v82, v82
	v_add_f32_e32 v249, v249, v81
	s_waitcnt lgkmcnt(8)
	v_mfma_f32_32x32x16_bf16 v[128:143], v[218:221], v[148:151], v[128:143]
	v_exp_f32_e32 v83, v83
	v_add_f32_e32 v250, v250, v82
	v_exp_f32_e32 v84, v84
	v_add_f32_e32 v251, v251, v83
	v_exp_f32_e32 v85, v85
	v_mfma_f32_32x32x16_bf16 v[112:127], v[222:225], v[148:151], v[112:127]
	ds_read_b128 v[218:221], v231 offset:96
	ds_read_b128 v[222:225], v231 offset:4704
	v_add_f32_e32 v248, v248, v84
	v_exp_f32_e32 v86, v86
	v_add_f32_e32 v249, v249, v85
	v_exp_f32_e32 v87, v87
	v_add_f32_e32 v250, v250, v86
	s_waitcnt lgkmcnt(8)
	v_mfma_f32_32x32x16_bf16 v[128:143], v[234:237], v[152:155], v[128:143]
	v_add_f32_e32 v251, v251, v87
	v_exp_f32_e32 v88, v88
	v_exp_f32_e32 v89, v89
	v_add_f32_e32 v248, v248, v88
	v_exp_f32_e32 v90, v90
	v_mfma_f32_32x32x16_bf16 v[112:127], v[238:241], v[152:155], v[112:127]
	v_add_f32_e32 v249, v249, v89
	v_exp_f32_e32 v91, v91
	v_add_f32_e32 v250, v250, v90
	v_exp_f32_e32 v92, v92
	v_add_f32_e32 v251, v251, v91
	s_waitcnt lgkmcnt(6)
	v_mfma_f32_32x32x16_bf16 v[64:79], v[2:5], v[96:99], v[64:79]
	v_exp_f32_e32 v93, v93
	v_add_f32_e32 v248, v248, v92
	v_exp_f32_e32 v94, v94
	v_add_f32_e32 v249, v249, v93
	v_mfma_f32_32x32x16_bf16 v[48:63], v[6:9], v[96:99], v[48:63]
	v_exp_f32_e32 v95, v95
	v_add_f32_e32 v250, v250, v94
	v_add_f32_e32 v251, v251, v95
	v_cvt_pk_bf16_f32 v234, v80, v81
	s_waitcnt lgkmcnt(4)
	v_mfma_f32_32x32x16_bf16 v[64:79], v[10:13], v[104:107], v[64:79]
	v_cvt_pk_bf16_f32 v235, v82, v83
	v_cvt_pk_bf16_f32 v236, v84, v85
	v_cvt_pk_bf16_f32 v237, v86, v87
	v_cvt_pk_bf16_f32 v238, v88, v89
	v_mfma_f32_32x32x16_bf16 v[48:63], v[198:201], v[104:107], v[48:63]
	v_cvt_pk_bf16_f32 v239, v90, v91
	v_cvt_pk_bf16_f32 v240, v92, v93
	v_cvt_pk_bf16_f32 v241, v94, v95
	s_mov_b32 s1, s30
	s_add_i32 s30, s30, 0x2400
	s_cmp_eq_u32 s30, 0x6c00
	s_cselect_b32 s30, 0, s30
	s_mov_b32 s31, s1
	v_add_u32_e32 v191, s90, v190
	v_add_u32_e32 v192, s30, v247
	s_cmp_eq_u32 s75, 3
	s_cbranch_scc1 .Lfa_as_w3
	s_cmp_eq_u32 s75, 2
	s_cbranch_scc1 .Lfa_as_w2
	s_waitcnt vmcnt(4)
	s_branch .Lfa_as_wj

; __device__ __forceinline__ void attn_unit(const Args& a, int l, int b, int h, int R0, bool special, LAS unsigned char* lds, float kb, int wv, bool pre, bool hasn, int nb, int nh, int nR0) {
;     ...
;     if (wave >= 4) __builtin_amdgcn_s_setprio(1);
.Lfa_as_wj:
	s_waitcnt lgkmcnt(0)
	s_barrier
	ds_read_b128 v[2:5], v191
	ds_read_b128 v[6:9], v191 offset:6656
	ds_read_b128 v[10:13], v191 offset:32
	ds_read_b128 v[198:201], v191 offset:6688
	ds_read_b128 v[202:205], v191 offset:64
	ds_read_b128 v[206:209], v191 offset:6720
	v_mfma_f32_32x32x16_bf16 v[64:79], v[210:213], v[234:237], v[64:79]
	v_mfma_f32_32x32x16_bf16 v[48:63], v[214:217], v[234:237], v[48:63]
	s_xor_b32 s1, s90, 0xa800
	s_add_i32 m0, s1, s66
	s_and_b64 vcc, exec, s[40:41]
	global_load_lds_dwordx4 v0, s[22:23]
	s_cbranch_vccnz .Lfa_bs_nok
	s_add_i32 m0, s1, s78
	s_and_b64 vcc, exec, s[42:43]
	global_load_lds_dwordx4 v14, s[22:23]
.Lfa_bs_nok:
	s_add_u32 s22, s22, 0x3000
	s_addc_u32 s23, s23, 0
	v_mfma_f32_32x32x16_bf16 v[64:79], v[218:221], v[238:241], v[64:79]
	ds_read_b128 v[210:213], v191 offset:96
	ds_read_b128 v[214:217], v191 offset:6752
	v_mfma_f32_32x32x16_bf16 v[48:63], v[222:225], v[238:241], v[48:63]
	ds_read_b128 v[218:221], v191 offset:128
	ds_read_b128 v[222:225], v191 offset:6784
	ds_read_b128 v[234:237], v191 offset:160
	ds_read_b128 v[238:241], v191 offset:6816
	s_add_i32 s1, s31, s66
	s_add_i32 m0, s1, 0xd000
	s_and_b64 vcc, exec, s[42:43]
	global_load_lds_dwordx4 v15, s[34:35]
	s_cbranch_vccnz .Lfa_bs_nov
	s_add_i32 m0, s31, 0xf000
	s_nop 0
	global_load_lds_dwordx4 v197, s[34:35]
.Lfa_bs_nov:
	s_add_u32 s34, s34, 0x80
	s_addc_u32 s35, s35, 0
	v_exp_f32_e32 v128, v128
	v_exp_f32_e32 v129, v129
	v_add_f32_e32 v248, v248, v128
	v_exp_f32_e32 v130, v130
	v_add_f32_e32 v249, v249, v129
	s_waitcnt lgkmcnt(10)
	v_mfma_f32_32x32x16_bf16 v[96:111], v[2:5], v[156:159], v[32:47]
	v_exp_f32_e32 v131, v131
	v_add_f32_e32 v250, v250, v130
	v_exp_f32_e32 v132, v132
	v_add_f32_e32 v251, v251, v131
	v_exp_f32_e32 v133, v133
	v_mfma_f32_32x32x16_bf16 v[80:95], v[6:9], v[156:159], v[32:47]
	ds_read_b128 v[2:5], v192
	ds_read_b128 v[6:9], v192 offset:4608
	v_add_f32_e32 v248, v248, v132
	v_exp_f32_e32 v134, v134
	v_add_f32_e32 v249, v249, v133
	v_exp_f32_e32 v135, v135
	v_add_f32_e32 v250, v250, v134
	s_waitcnt lgkmcnt(10)
	v_mfma_f32_32x32x16_bf16 v[96:111], v[10:13], v[160:163], v[96:111]
	v_add_f32_e32 v251, v251, v135
	v_cvt_pk_bf16_f32 v128, v128, v129
	v_cvt_pk_bf16_f32 v129, v130, v131
	v_cvt_pk_bf16_f32 v130, v132, v133
	v_cvt_pk_bf16_f32 v131, v134, v135
	v_mfma_f32_32x32x16_bf16 v[80:95], v[198:201], v[160:163], v[80:95]
	ds_read_b128 v[10:13], v192 offset:32
	ds_read_b128 v[198:201], v192 offset:4640
	v_exp_f32_e32 v136, v136
	v_exp_f32_e32 v137, v137
	v_add_f32_e32 v248, v248, v136
	v_exp_f32_e32 v138, v138
	v_add_f32_e32 v249, v249, v137
	s_waitcnt lgkmcnt(10)
	v_mfma_f32_32x32x16_bf16 v[96:111], v[202:205], v[164:167], v[96:111]
	v_exp_f32_e32 v139, v139
	v_add_f32_e32 v250, v250, v138
	v_exp_f32_e32 v140, v140
	v_add_f32_e32 v251, v251, v139
	v_exp_f32_e32 v141, v141
	v_mfma_f32_32x32x16_bf16 v[80:95], v[206:209], v[164:167], v[80:95]
	v_add_f32_e32 v248, v248, v140
	v_exp_f32_e32 v142, v142
	v_add_f32_e32 v249, v249, v141
	v_exp_f32_e32 v143, v143
	v_add_f32_e32 v250, v250, v142
	s_waitcnt lgkmcnt(8)
	v_mfma_f32_32x32x16_bf16 v[96:111], v[210:213], v[144:147], v[96:111]
	v_add_f32_e32 v251, v251, v143
	v_cvt_pk_bf16_f32 v136, v136, v137
	v_cvt_pk_bf16_f32 v137, v138, v139
	v_cvt_pk_bf16_f32 v138, v140, v141
	v_cvt_pk_bf16_f32 v139, v142, v143
	v_mfma_f32_32x32x16_bf16 v[80:95], v[214:217], v[144:147], v[80:95]
	ds_read_b128 v[210:213], v192 offset:64
	ds_read_b128 v[214:217], v192 offset:4672
	v_exp_f32_e32 v112, v112
	v_exp_f32_e32 v113, v113
	v_add_f32_e32 v248, v248, v112
	v_exp_f32_e32 v114, v114
	v_add_f32_e32 v249, v249, v113
	s_waitcnt lgkmcnt(8)
	v_mfma_f32_32x32x16_bf16 v[96:111], v[218:221], v[148:151], v[96:111]
	v_exp_f32_e32 v115, v115
	v_add_f32_e32 v250, v250, v114
	v_exp_f32_e32 v116, v116
	v_add_f32_e32 v251, v251, v115
	v_exp_f32_e32 v117, v117
	v_mfma_f32_32x32x16_bf16 v[80:95], v[222:225], v[148:151], v[80:95]
	ds_read_b128 v[218:221], v192 offset:96
	ds_read_b128 v[222:225], v192 offset:4704
	v_add_f32_e32 v248, v248, v116
	v_exp_f32_e32 v118, v118
	v_add_f32_e32 v249, v249, v117
	v_exp_f32_e32 v119, v119
	v_add_f32_e32 v250, v250, v118
	s_waitcnt lgkmcnt(8)
	v_mfma_f32_32x32x16_bf16 v[96:111], v[234:237], v[152:155], v[96:111]
	v_add_f32_e32 v251, v251, v119
	v_exp_f32_e32 v120, v120
	v_exp_f32_e32 v121, v121
	v_add_f32_e32 v248, v248, v120
	v_exp_f32_e32 v122, v122
	v_mfma_f32_32x32x16_bf16 v[80:95], v[238:241], v[152:155], v[80:95]
	v_add_f32_e32 v249, v249, v121
	v_exp_f32_e32 v123, v123
	v_add_f32_e32 v250, v250, v122
	v_exp_f32_e32 v124, v124
	v_add_f32_e32 v251, v251, v123
	s_waitcnt lgkmcnt(6)
	v_mfma_f32_32x32x16_bf16 v[64:79], v[2:5], v[128:131], v[64:79]
	v_exp_f32_e32 v125, v125
	v_add_f32_e32 v248, v248, v124
	v_exp_f32_e32 v126, v126
	v_add_f32_e32 v249, v249, v125
	v_mfma_f32_32x32x16_bf16 v[48:63], v[6:9], v[128:131], v[48:63]
	v_exp_f32_e32 v127, v127
	v_add_f32_e32 v250, v250, v126
	v_add_f32_e32 v251, v251, v127
	v_cvt_pk_bf16_f32 v234, v112, v113
	s_waitcnt lgkmcnt(4)
	v_mfma_f32_32x32x16_bf16 v[64:79], v[10:13], v[136:139], v[64:79]
	v_cvt_pk_bf16_f32 v235, v114, v115
	v_cvt_pk_bf16_f32 v236, v116, v117
	v_cvt_pk_bf16_f32 v237, v118, v119
	v_cvt_pk_bf16_f32 v238, v120, v121
	v_mfma_f32_32x32x16_bf16 v[48:63], v[198:201], v[136:139], v[48:63]
	v_cvt_pk_bf16_f32 v239, v122, v123
	v_cvt_pk_bf16_f32 v240, v124, v125
	v_cvt_pk_bf16_f32 v241, v126, v127
	s_mov_b32 s1, s30
	s_add_i32 s30, s30, 0x2400
	s_cmp_eq_u32 s30, 0x6c00
	s_cselect_b32 s30, 0, s30
	s_mov_b32 s31, s1
	s_xor_b32 s88, s88, 0x6800
	v_add_u32_e32 v230, s88, v190
	v_add_u32_e32 v231, s30, v247
	s_cmp_eq_u32 s75, 3
	s_cbranch_scc1 .Lfa_bs_w3
	s_cmp_eq_u32 s75, 2
	s_cbranch_scc1 .Lfa_bs_w2
	s_waitcnt vmcnt(4)
	s_branch .Lfa_bs_wj

; #define ATT_ISSUE(t) do { if ((t) + 3 <= TL) ATT_DMAK((t) + 3); if ((t) + 2 <= TL) ATT_DMAV((t) + 2); } while (0)
; #define ATT_SYNC(t) do { if ((t) + 3 <= TL) { if (nis == 4) asm volatile("s_waitcnt vmcnt(4)" ::: "memory"); else if (nis == 3) asm volatile("s_waitcnt vmcnt(3)" ::: "memory"); else asm volatile("s_waitcnt vmcnt(2)" ::: "memory"); } \
;         else asm volatile("s_waitcnt vmcnt(0)" ::: "memory"); \
;         LDS_WAIT(); __builtin_amdgcn_s_barrier(); asm volatile("" ::: "memory"); } while (0)
; #define ATT_TAIL(t, C0, C1) do { ATT_ISSUE(t); bf16x8 vf[8], pa[4]; ATT_LDV(t); ATT_EXPP(C0, C1); ATT_PV(); ATT_SYNC(t); } while (0)
; __device__ __forceinline__ void attn_unit(const Args& a, int l, int b, int h, int R0, bool special, LAS unsigned char* lds, float kb, int wv, bool pre, bool hasn, int nb, int nh, int nR0) {
;     ...
;     {
;         f32x16 pb0, pb1; int t = 1;
;         for (; t + 1 < tw; t += 2) { ATT_BODY(t, pc0, pc1, pb0, pb1); ATT_BODY(t + 1, pb0, pb1, pc0, pc1); }
;         if (t < tw) { ATT_BODY(t, pc0, pc1, pb0, pb1); ++t; ATT_TAIL(t, pb0, pb1); ++t; }
;         else if (t == tw) { ATT_TAIL(t, pc0, pc1); ++t; }
;         for (; t <= TL; ++t) { ATT_ISSUE(t); ATT_SYNC(t); }
.Lfa_bs_wj:
	s_waitcnt lgkmcnt(0)
	s_barrier
	s_addk_i32 s83, 0x4800
	s_addk_i32 s84, 0x80
	s_addk_i32 s85, 0x4800
	s_add_i32 s79, s79, 2
	s_add_i32 s86, s86, 2
	s_add_i32 s80, s80, 2
	s_add_i32 s32, s32, 1
	s_xor_b32 s90, s90, 0xa800
	s_mov_b32 s87, s76
	s_add_i32 s0, s76, 2
	s_cmp_le_i32 s0, s24
	s_cbranch_scc1 .Lfa_sloop
	s_cmp_lt_i32 s76, s77
	s_cbranch_scc0 .Lfa_exit
.Lfa_loop:
	s_add_i32 s76, s87, 2
	ds_read_b128 v[2:5], v230
	ds_read_b128 v[6:9], v230 offset:6656
	ds_read_b128 v[10:13], v230 offset:32
	ds_read_b128 v[198:201], v230 offset:6688
	ds_read_b128 v[202:205], v230 offset:64
	ds_read_b128 v[206:209], v230 offset:6720
	v_mfma_f32_32x32x16_bf16 v[64:79], v[210:213], v[234:237], v[64:79]
	v_mfma_f32_32x32x16_bf16 v[48:63], v[214:217], v[234:237], v[48:63]
	s_mov_b32 s96, 0
	s_cmp_gt_u32 s76, s73
	s_cbranch_scc1 .Lfa_a_nok
	s_xor_b32 s1, s88, 0x6800
	s_add_i32 m0, s1, s66
	s_mov_b32 s96, s75
	global_load_lds_dwordx4 v0, s[22:23]
	s_and_b64 vcc, exec, s[40:41]
	s_cbranch_vccnz .Lfa_a_nok
	s_add_i32 m0, s1, s78
	s_and_b64 vcc, exec, s[42:43]
	global_load_lds_dwordx4 v14, s[22:23]
.Lfa_a_nok:
	s_add_u32 s22, s22, 0x3000
	s_addc_u32 s23, s23, 0
	v_mfma_f32_32x32x16_bf16 v[64:79], v[218:221], v[238:241], v[64:79]
	ds_read_b128 v[210:213], v230 offset:96
	ds_read_b128 v[214:217], v230 offset:6752
	v_mfma_f32_32x32x16_bf16 v[48:63], v[222:225], v[238:241], v[48:63]
	ds_read_b128 v[218:221], v230 offset:128
	ds_read_b128 v[222:225], v230 offset:6784
	ds_read_b128 v[234:237], v230 offset:160
	ds_read_b128 v[238:241], v230 offset:6816
	s_add_i32 s1, s87, 1
	s_cmp_gt_u32 s1, s73
	s_cbranch_scc1 .Lfa_a_nov
	s_add_i32 s1, s31, s66
	s_add_i32 m0, s1, 0xd000
	s_and_b64 vcc, exec, s[42:43]
	global_load_lds_dwordx4 v15, s[34:35]
	s_cbranch_vccnz .Lfa_a_nov
	s_add_i32 m0, s31, 0xf000
	s_nop 0
	global_load_lds_dwordx4 v197, s[34:35]
.Lfa_a_nov:
	s_add_u32 s34, s34, 0x80
	s_addc_u32 s35, s35, 0
	v_exp_f32_e32 v96, v96
	v_exp_f32_e32 v97, v97
	v_add_f32_e32 v248, v248, v96
	v_exp_f32_e32 v98, v98
	v_add_f32_e32 v249, v249, v97
	s_waitcnt lgkmcnt(10)
	v_mfma_f32_32x32x16_bf16 v[128:143], v[2:5], v[156:159], v[32:47]
	v_exp_f32_e32 v99, v99
	v_add_f32_e32 v250, v250, v98
	v_exp_f32_e32 v100, v100
	v_add_f32_e32 v251, v251, v99
	v_exp_f32_e32 v101, v101
	v_mfma_f32_32x32x16_bf16 v[112:127], v[6:9], v[156:159], v[32:47]
	ds_read_b128 v[2:5], v231
	ds_read_b128 v[6:9], v231 offset:4608
	v_add_f32_e32 v248, v248, v100
	v_exp_f32_e32 v102, v102
	v_add_f32_e32 v249, v249, v101
	v_exp_f32_e32 v103, v103
	v_add_f32_e32 v250, v250, v102
	s_waitcnt lgkmcnt(10)
	v_mfma_f32_32x32x16_bf16 v[128:143], v[10:13], v[160:163], v[128:143]
	v_add_f32_e32 v251, v251, v103
	v_cvt_pk_bf16_f32 v96, v96, v97
	v_cvt_pk_bf16_f32 v97, v98, v99
	v_cvt_pk_bf16_f32 v98, v100, v101
	v_cvt_pk_bf16_f32 v99, v102, v103
	v_mfma_f32_32x32x16_bf16 v[112:127], v[198:201], v[160:163], v[112:127]
	ds_read_b128 v[10:13], v231 offset:32
	ds_read_b128 v[198:201], v231 offset:4640
	v_exp_f32_e32 v104, v104
	v_exp_f32_e32 v105, v105
	v_add_f32_e32 v248, v248, v104
	v_exp_f32_e32 v106, v106
	v_add_f32_e32 v249, v249, v105
	s_waitcnt lgkmcnt(10)
	v_mfma_f32_32x32x16_bf16 v[128:143], v[202:205], v[164:167], v[128:143]
	v_exp_f32_e32 v107, v107
	v_add_f32_e32 v250, v250, v106
	v_exp_f32_e32 v108, v108
	v_add_f32_e32 v251, v251, v107
	v_exp_f32_e32 v109, v109
	v_mfma_f32_32x32x16_bf16 v[112:127], v[206:209], v[164:167], v[112:127]
	v_add_f32_e32 v248, v248, v108
	v_exp_f32_e32 v110, v110
	v_add_f32_e32 v249, v249, v109
	v_exp_f32_e32 v111, v111
	v_add_f32_e32 v250, v250, v110
	s_waitcnt lgkmcnt(8)
	v_mfma_f32_32x32x16_bf16 v[128:143], v[210:213], v[144:147], v[128:143]
	v_add_f32_e32 v251, v251, v111
	v_cvt_pk_bf16_f32 v104, v104, v105
	v_cvt_pk_bf16_f32 v105, v106, v107
	v_cvt_pk_bf16_f32 v106, v108, v109
	v_cvt_pk_bf16_f32 v107, v110, v111
	v_mfma_f32_32x32x16_bf16 v[112:127], v[214:217], v[144:147], v[112:127]
	ds_read_b128 v[210:213], v231 offset:64
	ds_read_b128 v[214:217], v231 offset:4672
	v_exp_f32_e32 v80, v80
	v_exp_f32_e32 v81, v81
	v_add_f32_e32 v248, v248, v80
	v_exp_f32_e32 v82, v82
	v_add_f32_e32 v249, v249, v81
	s_waitcnt lgkmcnt(8)
	v_mfma_f32_32x32x16_bf16 v[128:143], v[218:221], v[148:151], v[128:143]
	v_exp_f32_e32 v83, v83
	v_add_f32_e32 v250, v250, v82
	v_exp_f32_e32 v84, v84
	v_add_f32_e32 v251, v251, v83
	v_exp_f32_e32 v85, v85
	v_mfma_f32_32x32x16_bf16 v[112:127], v[222:225], v[148:151], v[112:127]
	ds_read_b128 v[218:221], v231 offset:96
	ds_read_b128 v[222:225], v231 offset:4704
	v_add_f32_e32 v248, v248, v84
	v_exp_f32_e32 v86, v86
	v_add_f32_e32 v249, v249, v85
	v_exp_f32_e32 v87, v87
	v_add_f32_e32 v250, v250, v86
	s_waitcnt lgkmcnt(8)
	v_mfma_f32_32x32x16_bf16 v[128:143], v[234:237], v[152:155], v[128:143]
	v_add_f32_e32 v251, v251, v87
	v_exp_f32_e32 v88, v88
	v_exp_f32_e32 v89, v89
	v_add_f32_e32 v248, v248, v88
	v_exp_f32_e32 v90, v90
	v_mfma_f32_32x32x16_bf16 v[112:127], v[238:241], v[152:155], v[112:127]
	v_add_f32_e32 v249, v249, v89
	v_exp_f32_e32 v91, v91
	v_add_f32_e32 v250, v250, v90
	v_exp_f32_e32 v92, v92
	v_add_f32_e32 v251, v251, v91
	s_waitcnt lgkmcnt(6)
	v_mfma_f32_32x32x16_bf16 v[64:79], v[2:5], v[96:99], v[64:79]
	v_exp_f32_e32 v93, v93
	v_add_f32_e32 v248, v248, v92
	v_exp_f32_e32 v94, v94
	v_add_f32_e32 v249, v249, v93
	v_mfma_f32_32x32x16_bf16 v[48:63], v[6:9], v[96:99], v[48:63]
	v_exp_f32_e32 v95, v95
	v_add_f32_e32 v250, v250, v94
	v_add_f32_e32 v251, v251, v95
	v_cvt_pk_bf16_f32 v234, v80, v81
	s_waitcnt lgkmcnt(4)
	v_mfma_f32_32x32x16_bf16 v[64:79], v[10:13], v[104:107], v[64:79]
	v_cvt_pk_bf16_f32 v235, v82, v83
	v_cvt_pk_bf16_f32 v236, v84, v85
	v_cvt_pk_bf16_f32 v237, v86, v87
	v_cvt_pk_bf16_f32 v238, v88, v89
	v_mfma_f32_32x32x16_bf16 v[48:63], v[198:201], v[104:107], v[48:63]
	v_cvt_pk_bf16_f32 v239, v90, v91
	v_cvt_pk_bf16_f32 v240, v92, v93
	v_cvt_pk_bf16_f32 v241, v94, v95
	s_mov_b32 s1, s30
	s_add_i32 s30, s30, 0x2400
	s_cmp_eq_u32 s30, 0x6c00
	s_cselect_b32 s30, 0, s30
	s_mov_b32 s31, s1
	v_add_u32_e32 v191, s90, v190
	v_add_u32_e32 v192, s30, v247
	s_sub_i32 s0, s84, 64
	s_cmp_le_i32 s0, s74
	s_cbranch_scc0 .Lfa_mask_a

; __device__ __forceinline__ void attn_unit(const Args& a, int l, int b, int h, int R0, bool special, LAS unsigned char* lds, float kb, int wv, bool pre, bool hasn, int nb, int nh, int nR0) {
;     ...
;     if (wave >= 4) __builtin_amdgcn_s_setprio(1);
.Lfa_a_wj:
	s_waitcnt lgkmcnt(0)
	s_barrier
	ds_read_b128 v[2:5], v191
	ds_read_b128 v[6:9], v191 offset:6656
	ds_read_b128 v[10:13], v191 offset:32
	ds_read_b128 v[198:201], v191 offset:6688
	ds_read_b128 v[202:205], v191 offset:64
	ds_read_b128 v[206:209], v191 offset:6720
	v_mfma_f32_32x32x16_bf16 v[64:79], v[210:213], v[234:237], v[64:79]
	v_mfma_f32_32x32x16_bf16 v[48:63], v[214:217], v[234:237], v[48:63]
	s_mov_b32 s96, 0
	s_add_i32 s1, s76, 1
	s_cmp_gt_u32 s1, s73
	s_cbranch_scc1 .Lfa_b_nok
	s_xor_b32 s1, s90, 0xa800
	s_add_i32 m0, s1, s66
	s_mov_b32 s96, s75
	global_load_lds_dwordx4 v0, s[22:23]
	s_and_b64 vcc, exec, s[40:41]
	s_cbranch_vccnz .Lfa_b_nok
	s_add_i32 m0, s1, s78
	s_and_b64 vcc, exec, s[42:43]
	global_load_lds_dwordx4 v14, s[22:23]
.Lfa_b_nok:
	s_add_u32 s22, s22, 0x3000
	s_addc_u32 s23, s23, 0
	v_mfma_f32_32x32x16_bf16 v[64:79], v[218:221], v[238:241], v[64:79]
	ds_read_b128 v[210:213], v191 offset:96
	ds_read_b128 v[214:217], v191 offset:6752
	v_mfma_f32_32x32x16_bf16 v[48:63], v[222:225], v[238:241], v[48:63]
	ds_read_b128 v[218:221], v191 offset:128
	ds_read_b128 v[222:225], v191 offset:6784
	ds_read_b128 v[234:237], v191 offset:160
	ds_read_b128 v[238:241], v191 offset:6816
	s_cmp_gt_u32 s76, s73
	s_cbranch_scc1 .Lfa_b_nov
	s_add_i32 s1, s31, s66
	s_add_i32 m0, s1, 0xd000
	s_and_b64 vcc, exec, s[42:43]
	global_load_lds_dwordx4 v15, s[34:35]
	s_cbranch_vccnz .Lfa_b_nov
	s_add_i32 m0, s31, 0xf000
	s_nop 0
	global_load_lds_dwordx4 v197, s[34:35]
.Lfa_b_nov:
	s_add_u32 s34, s34, 0x80
	s_addc_u32 s35, s35, 0
	v_exp_f32_e32 v128, v128
	v_exp_f32_e32 v129, v129
	v_add_f32_e32 v248, v248, v128
	v_exp_f32_e32 v130, v130
	v_add_f32_e32 v249, v249, v129
	s_waitcnt lgkmcnt(10)
	v_mfma_f32_32x32x16_bf16 v[96:111], v[2:5], v[156:159], v[32:47]
	v_exp_f32_e32 v131, v131
	v_add_f32_e32 v250, v250, v130
	v_exp_f32_e32 v132, v132
	v_add_f32_e32 v251, v251, v131
	v_exp_f32_e32 v133, v133
	v_mfma_f32_32x32x16_bf16 v[80:95], v[6:9], v[156:159], v[32:47]
	ds_read_b128 v[2:5], v192
	ds_read_b128 v[6:9], v192 offset:4608
	v_add_f32_e32 v248, v248, v132
	v_exp_f32_e32 v134, v134
	v_add_f32_e32 v249, v249, v133
	v_exp_f32_e32 v135, v135
	v_add_f32_e32 v250, v250, v134
	s_waitcnt lgkmcnt(10)
	v_mfma_f32_32x32x16_bf16 v[96:111], v[10:13], v[160:163], v[96:111]
	v_add_f32_e32 v251, v251, v135
	v_cvt_pk_bf16_f32 v128, v128, v129
	v_cvt_pk_bf16_f32 v129, v130, v131
	v_cvt_pk_bf16_f32 v130, v132, v133
	v_cvt_pk_bf16_f32 v131, v134, v135
	v_mfma_f32_32x32x16_bf16 v[80:95], v[198:201], v[160:163], v[80:95]
	ds_read_b128 v[10:13], v192 offset:32
	ds_read_b128 v[198:201], v192 offset:4640
	v_exp_f32_e32 v136, v136
	v_exp_f32_e32 v137, v137
	v_add_f32_e32 v248, v248, v136
	v_exp_f32_e32 v138, v138
	v_add_f32_e32 v249, v249, v137
	s_waitcnt lgkmcnt(10)
	v_mfma_f32_32x32x16_bf16 v[96:111], v[202:205], v[164:167], v[96:111]
	v_exp_f32_e32 v139, v139
	v_add_f32_e32 v250, v250, v138
	v_exp_f32_e32 v140, v140
	v_add_f32_e32 v251, v251, v139
	v_exp_f32_e32 v141, v141
	v_mfma_f32_32x32x16_bf16 v[80:95], v[206:209], v[164:167], v[80:95]
	v_add_f32_e32 v248, v248, v140
	v_exp_f32_e32 v142, v142
	v_add_f32_e32 v249, v249, v141
	v_exp_f32_e32 v143, v143
	v_add_f32_e32 v250, v250, v142
	s_waitcnt lgkmcnt(8)
	v_mfma_f32_32x32x16_bf16 v[96:111], v[210:213], v[144:147], v[96:111]
	v_add_f32_e32 v251, v251, v143
	v_cvt_pk_bf16_f32 v136, v136, v137
	v_cvt_pk_bf16_f32 v137, v138, v139
	v_cvt_pk_bf16_f32 v138, v140, v141
	v_cvt_pk_bf16_f32 v139, v142, v143
	v_mfma_f32_32x32x16_bf16 v[80:95], v[214:217], v[144:147], v[80:95]
	ds_read_b128 v[210:213], v192 offset:64
	ds_read_b128 v[214:217], v192 offset:4672
	v_exp_f32_e32 v112, v112
	v_exp_f32_e32 v113, v113
	v_add_f32_e32 v248, v248, v112
	v_exp_f32_e32 v114, v114
	v_add_f32_e32 v249, v249, v113
	s_waitcnt lgkmcnt(8)
	v_mfma_f32_32x32x16_bf16 v[96:111], v[218:221], v[148:151], v[96:111]
	v_exp_f32_e32 v115, v115
	v_add_f32_e32 v250, v250, v114
	v_exp_f32_e32 v116, v116
	v_add_f32_e32 v251, v251, v115
	v_exp_f32_e32 v117, v117
	v_mfma_f32_32x32x16_bf16 v[80:95], v[222:225], v[148:151], v[80:95]
	ds_read_b128 v[218:221], v192 offset:96
	ds_read_b128 v[222:225], v192 offset:4704
	v_add_f32_e32 v248, v248, v116
	v_exp_f32_e32 v118, v118
	v_add_f32_e32 v249, v249, v117
	v_exp_f32_e32 v119, v119
	v_add_f32_e32 v250, v250, v118
	s_waitcnt lgkmcnt(8)
	v_mfma_f32_32x32x16_bf16 v[96:111], v[234:237], v[152:155], v[96:111]
	v_add_f32_e32 v251, v251, v119
	v_exp_f32_e32 v120, v120
	v_exp_f32_e32 v121, v121
	v_add_f32_e32 v248, v248, v120
	v_exp_f32_e32 v122, v122
	v_mfma_f32_32x32x16_bf16 v[80:95], v[238:241], v[152:155], v[80:95]
	v_add_f32_e32 v249, v249, v121
	v_exp_f32_e32 v123, v123
	v_add_f32_e32 v250, v250, v122
	v_exp_f32_e32 v124, v124
	v_add_f32_e32 v251, v251, v123
	s_waitcnt lgkmcnt(6)
	v_mfma_f32_32x32x16_bf16 v[64:79], v[2:5], v[128:131], v[64:79]
	v_exp_f32_e32 v125, v125
	v_add_f32_e32 v248, v248, v124
	v_exp_f32_e32 v126, v126
	v_add_f32_e32 v249, v249, v125
	v_mfma_f32_32x32x16_bf16 v[48:63], v[6:9], v[128:131], v[48:63]
	v_exp_f32_e32 v127, v127
	v_add_f32_e32 v250, v250, v126
	v_add_f32_e32 v251, v251, v127
	v_cvt_pk_bf16_f32 v234, v112, v113
	s_waitcnt lgkmcnt(4)
	v_mfma_f32_32x32x16_bf16 v[64:79], v[10:13], v[136:139], v[64:79]
	v_cvt_pk_bf16_f32 v235, v114, v115
	v_cvt_pk_bf16_f32 v236, v116, v117
	v_cvt_pk_bf16_f32 v237, v118, v119
	v_cvt_pk_bf16_f32 v238, v120, v121
	v_mfma_f32_32x32x16_bf16 v[48:63], v[198:201], v[136:139], v[48:63]
	v_cvt_pk_bf16_f32 v239, v122, v123
	v_cvt_pk_bf16_f32 v240, v124, v125
	v_cvt_pk_bf16_f32 v241, v126, v127
	s_mov_b32 s1, s30
	s_add_i32 s30, s30, 0x2400
	s_cmp_eq_u32 s30, 0x6c00
	s_cselect_b32 s30, 0, s30
	s_mov_b32 s31, s1
	s_xor_b32 s88, s88, 0x6800
	v_add_u32_e32 v230, s88, v190
	v_add_u32_e32 v231, s30, v247
	s_cmp_le_i32 s84, s74
	s_cbranch_scc0 .Lfa_mask_b

; #define ATT_ISSUE(t) do { if ((t) + 3 <= TL) ATT_DMAK((t) + 3); if ((t) + 2 <= TL) ATT_DMAV((t) + 2); } while (0)
; #define ATT_SYNC(t) do { if ((t) + 3 <= TL) { if (nis == 4) asm volatile("s_waitcnt vmcnt(4)" ::: "memory"); else if (nis == 3) asm volatile("s_waitcnt vmcnt(3)" ::: "memory"); else asm volatile("s_waitcnt vmcnt(2)" ::: "memory"); } \
;         else asm volatile("s_waitcnt vmcnt(0)" ::: "memory"); \
;         LDS_WAIT(); __builtin_amdgcn_s_barrier(); asm volatile("" ::: "memory"); } while (0)
; #define ATT_TAIL(t, C0, C1) do { ATT_ISSUE(t); bf16x8 vf[8], pa[4]; ATT_LDV(t); ATT_EXPP(C0, C1); ATT_PV(); ATT_SYNC(t); } while (0)
; __device__ __forceinline__ void attn_unit(const Args& a, int l, int b, int h, int R0, bool special, LAS unsigned char* lds, float kb, int wv, bool pre, bool hasn, int nb, int nh, int nR0) {
;     ...
;         f32x16 pb0, pb1; int t = 1;
;         for (; t + 1 < tw; t += 2) { ATT_BODY(t, pc0, pc1, pb0, pb1); ATT_BODY(t + 1, pb0, pb1, pc0, pc1); }
;         if (t < tw) { ATT_BODY(t, pc0, pc1, pb0, pb1); ++t; ATT_TAIL(t, pb0, pb1); ++t; }
;         else if (t == tw) { ATT_TAIL(t, pc0, pc1); ++t; }
;         for (; t <= TL; ++t) { ATT_ISSUE(t); ATT_SYNC(t); }
;     }
.Lfa_b_wj:
	s_waitcnt lgkmcnt(0)
	s_barrier
	s_addk_i32 s83, 0x4800
	s_addk_i32 s84, 0x80
	s_addk_i32 s85, 0x4800
	s_add_i32 s79, s79, 2
	s_add_i32 s86, s86, 2
	s_add_i32 s80, s80, 2
	s_add_i32 s32, s32, 1
	s_xor_b32 s90, s90, 0xa800
	s_cmp_lt_i32 s76, s77
	s_cbranch_scc0 .Lfa_exit
	s_mov_b32 s87, s76
	s_branch .Lfa_loop
